# docs 7.5 packed->scalar: the compiler's v_pk_fma_f32 group in the GQA/MLA loops split into scalar v_fmamk (base v31: all four groups scalar)
# speedup vs baseline: 1.0025x; 1.0025x over previous
.LBB0_702:
	v_cndmask_b32_e64 v110, v106, v149, s[8:9]
	v_mul_f32_e32 v94, 0xbe38aa3b, v110
	v_mov_b32_e32 v95, v94
	v_fmamk_f32 v50, v50, 0x3e38aa3b, v94
	v_fmamk_f32 v51, v51, 0x3e38aa3b, v94
	v_fmamk_f32 v52, v52, 0x3e38aa3b, v94
	v_fmamk_f32 v53, v53, 0x3e38aa3b, v94
	v_fmamk_f32 v54, v54, 0x3e38aa3b, v94
	v_fmamk_f32 v55, v55, 0x3e38aa3b, v94
	v_fmamk_f32 v56, v56, 0x3e38aa3b, v94
	v_fmamk_f32 v57, v57, 0x3e38aa3b, v94
	v_fmamk_f32 v58, v58, 0x3e38aa3b, v94
	v_fmamk_f32 v59, v59, 0x3e38aa3b, v94
	v_fmamk_f32 v60, v60, 0x3e38aa3b, v94
	v_fmamk_f32 v61, v61, 0x3e38aa3b, v94
	v_fmamk_f32 v62, v62, 0x3e38aa3b, v94
	v_fmamk_f32 v63, v63, 0x3e38aa3b, v94
	v_fmamk_f32 v64, v64, 0x3e38aa3b, v94
	v_fmac_f32_e32 v95, 0x3e38aa3b, v65
	v_exp_f32_e32 v120, v50
	v_exp_f32_e32 v128, v51
	v_exp_f32_e32 v121, v52
	v_exp_f32_e32 v129, v53
	v_exp_f32_e32 v126, v54
	v_exp_f32_e32 v149, v55
	v_exp_f32_e32 v127, v56
	v_exp_f32_e32 v150, v57
	v_exp_f32_e32 v112, v58
	v_exp_f32_e32 v115, v59
	v_exp_f32_e32 v113, v60
	v_exp_f32_e32 v116, v61
	v_exp_f32_e32 v114, v62
	v_exp_f32_e32 v117, v63
	v_exp_f32_e32 v118, v64
	v_exp_f32_e32 v119, v95
	v_fmamk_f32 v108, v34, 0x3e38aa3b, v94
	v_fmamk_f32 v109, v35, 0x3e38aa3b, v94
	v_add_f32_e32 v34, v146, v147
	v_fmac_f32_e32 v34, v145, v136
	v_add_f32_e32 v136, v151, v152
	v_fmamk_f32 v106, v36, 0x3e38aa3b, v94
	v_fmamk_f32 v107, v37, 0x3e38aa3b, v94
	v_fmamk_f32 v102, v38, 0x3e38aa3b, v94
	v_fmamk_f32 v103, v39, 0x3e38aa3b, v94
	v_fmamk_f32 v98, v40, 0x3e38aa3b, v94
	v_fmamk_f32 v99, v41, 0x3e38aa3b, v94
	v_fmamk_f32 v96, v42, 0x3e38aa3b, v94
	v_fmamk_f32 v97, v43, 0x3e38aa3b, v94
	v_fmamk_f32 v104, v44, 0x3e38aa3b, v94
	v_fmamk_f32 v105, v45, 0x3e38aa3b, v94
	v_fmamk_f32 v100, v46, 0x3e38aa3b, v94
	v_fmamk_f32 v101, v47, 0x3e38aa3b, v94
	v_fmamk_f32 v95, v49, 0x3e38aa3b, v94
	v_fmamk_f32 v94, v48, 0x3e38aa3b, v94
	v_fmac_f32_e32 v136, v34, v148
	v_lshl_add_u64 v[122:123], v[122:123], 0, s[24:25]
	v_lshl_add_u64 v[124:125], v[124:125], 0, s[24:25]
	s_add_i32 s19, s19, 2
	s_and_b64 vcc, exec, s[10:11]
	s_waitcnt lgkmcnt(0)
	s_barrier
	s_cbranch_vccnz .LBB0_783
	v_mov_b32_e32 v145, v111
	s_branch .LBB0_692

.LBB0_929:
	v_cndmask_b32_e64 v118, v114, v159, s[8:9]
	v_mul_f32_e32 v102, 0xbe16c740, v118
	v_mov_b32_e32 v103, v102
	v_fmamk_f32 v50, v50, 0x3e16c740, v102
	v_fmamk_f32 v51, v51, 0x3e16c740, v102
	v_fmamk_f32 v52, v52, 0x3e16c740, v102
	v_fmamk_f32 v53, v53, 0x3e16c740, v102
	v_fmamk_f32 v54, v54, 0x3e16c740, v102
	v_fmamk_f32 v55, v55, 0x3e16c740, v102
	v_fmamk_f32 v56, v56, 0x3e16c740, v102
	v_fmamk_f32 v57, v57, 0x3e16c740, v102
	v_fmamk_f32 v58, v58, 0x3e16c740, v102
	v_fmamk_f32 v59, v59, 0x3e16c740, v102
	v_fmamk_f32 v60, v60, 0x3e16c740, v102
	v_fmamk_f32 v61, v61, 0x3e16c740, v102
	v_fmamk_f32 v62, v62, 0x3e16c740, v102
	v_fmamk_f32 v63, v63, 0x3e16c740, v102
	v_fmamk_f32 v64, v64, 0x3e16c740, v102
	v_fmac_f32_e32 v103, 0x3e16c740, v65
	v_exp_f32_e32 v128, v50
	v_exp_f32_e32 v138, v51
	v_exp_f32_e32 v129, v52
	v_exp_f32_e32 v139, v53
	v_exp_f32_e32 v136, v54
	v_exp_f32_e32 v159, v55
	v_exp_f32_e32 v137, v56
	v_exp_f32_e32 v160, v57
	v_exp_f32_e32 v120, v58
	v_exp_f32_e32 v123, v59
	v_exp_f32_e32 v121, v60
	v_exp_f32_e32 v124, v61
	v_exp_f32_e32 v122, v62
	v_exp_f32_e32 v125, v63
	v_exp_f32_e32 v126, v64
	v_exp_f32_e32 v127, v103
	v_fmamk_f32 v116, v34, 0x3e16c740, v102
	v_fmamk_f32 v117, v35, 0x3e16c740, v102
	v_add_f32_e32 v34, v156, v157
	v_fmac_f32_e32 v34, v155, v144
	v_add_f32_e32 v144, v161, v162
	v_fmamk_f32 v114, v36, 0x3e16c740, v102
	v_fmamk_f32 v115, v37, 0x3e16c740, v102
	v_fmamk_f32 v110, v38, 0x3e16c740, v102
	v_fmamk_f32 v111, v39, 0x3e16c740, v102
	v_fmamk_f32 v106, v40, 0x3e16c740, v102
	v_fmamk_f32 v107, v41, 0x3e16c740, v102
	v_fmamk_f32 v104, v42, 0x3e16c740, v102
	v_fmamk_f32 v105, v43, 0x3e16c740, v102
	v_fmamk_f32 v112, v44, 0x3e16c740, v102
	v_fmamk_f32 v113, v45, 0x3e16c740, v102
	v_fmamk_f32 v108, v46, 0x3e16c740, v102
	v_fmamk_f32 v109, v47, 0x3e16c740, v102
	v_fmamk_f32 v103, v49, 0x3e16c740, v102
	v_fmamk_f32 v102, v48, 0x3e16c740, v102
	v_fmac_f32_e32 v144, v34, v158
	s_add_i32 s24, s24, 2
	v_lshl_add_u64 v[132:133], v[132:133], 0, s[2:3]
	v_lshl_add_u64 v[134:135], v[134:135], 0, s[2:3]
	s_and_b64 vcc, exec, s[16:17]
	s_waitcnt lgkmcnt(0)
	s_barrier
	s_cbranch_vccnz .LBB0_932
	v_mov_b32_e32 v155, v119
	s_branch .LBB0_919
